# phase 10 top-k: 169 compare/select pairs rotated over three spare SGPR pairs (no wait states between v_cmp and v_cndmask) + phase 11a lane exchanges as v_add_f32_dpp
# speedup vs baseline: 1.0011x; 1.0011x over previous
.LBB0_841:
	s_or_b64 exec, exec, s[28:29]
	v_cmp_gt_i32_e32 vcc, 0, v61
	v_mov_b32_e32 v106, 0
	s_nop 0
	v_cndmask_b32_e32 v64, -1, v101, vcc
	v_cmp_gt_i32_e32 vcc, 0, v77
	v_bitop3_b32 v64, v64, v61, s43 bitop3:0x78
	s_nop 0
	v_cndmask_b32_e32 v65, -1, v101, vcc
	v_cmp_lt_i32_e32 vcc, -1, v78
	v_bitop3_b32 v65, v65, v77, s43 bitop3:0x78
	s_nop 0
	v_cndmask_b32_e64 v66, v101, -1, vcc
	v_cmp_lt_i32_e32 vcc, -1, v80
	v_bitop3_b32 v66, v66, v78, s43 bitop3:0x78
	s_nop 0
	v_cndmask_b32_e64 v67, v101, -1, vcc
	v_cmp_lt_i32_e32 vcc, -1, v59
	v_bitop3_b32 v67, v67, v80, s43 bitop3:0x78
	s_nop 0
	v_cndmask_b32_e64 v61, v101, -1, vcc
	v_bitop3_b32 v68, v61, v59, s43 bitop3:0x78
	s_and_saveexec_b64 s[28:29], s[14:15]
	v_add_f32_e32 v59, v66, v68
	v_not_b32_e32 v61, v59
	v_or_b32_e32 v77, 0x80000000, v59
	v_cmp_gt_i32_e32 vcc, 0, v59
	s_nop 1
	v_cndmask_b32_e32 v59, v77, v61, vcc
	v_and_b32_e32 v59, 0xffffff00, v59
	v_or_b32_e32 v106, 0xbd, v59
	s_or_b64 exec, exec, s[28:29]
	v_pk_add_f32 v[108:109], v[64:65], v[68:69] op_sel_hi:[1,0]
	v_pk_add_f32 v[66:67], v[62:63], v[66:67] op_sel_hi:[0,1]
	v_and_b32_e32 v111, 0x7fffffff, v109
	v_and_b32_e32 v110, 0x7fffffff, v108
	v_xor_b32_e32 v59, -1, v109
	v_pk_add_f32 v[110:111], v[110:111], 0 neg_lo:[1,1] neg_hi:[1,1]
	v_cmp_gt_i32_e32 vcc, 0, v109
	v_xor_b32_e32 v61, -1, v108
	v_or_b32_e32 v107, 0x80000000, v67
	v_cndmask_b32_e32 v59, v111, v59, vcc
	v_cmp_gt_i32_e32 vcc, 0, v108
	v_and_b32_e32 v59, 0xffffff00, v59
	v_sub_u32_e32 v59, v59, v57
	v_cndmask_b32_e32 v61, v110, v61, vcc
	v_cmp_lt_i32_e32 vcc, -1, v69
	v_add_u32_e32 v77, 0xbe, v59
	v_pk_add_f32 v[108:109], v[62:63], v[64:65] op_sel_hi:[0,1]
	v_cndmask_b32_e64 v59, v101, -1, vcc
	v_not_b32_e32 v62, v67
	v_cmp_gt_i32_e32 vcc, 0, v67
	v_bitop3_b32 v68, v59, v69, s43 bitop3:0x78
	v_not_b32_e32 v59, v66
	v_or_b32_e32 v80, 0x80000000, v66
	v_cndmask_b32_e32 v62, v107, v62, vcc
	v_cmp_gt_i32_e32 vcc, 0, v66
	v_not_b32_e32 v78, v109
	v_or_b32_e32 v111, 0x80000000, v109
	v_cndmask_b32_e32 v59, v80, v59, vcc
	v_cmp_gt_i32_e32 vcc, 0, v109
	v_not_b32_e32 v69, v108
	v_or_b32_e32 v110, 0x80000000, v108
	v_cndmask_b32_e32 v66, v111, v78, vcc
	v_cmp_gt_i32_e32 vcc, 0, v108
	v_and_b32_e32 v59, 0xffffff00, v59
	v_sub_u32_e32 v59, v59, v2
	v_cndmask_b32_e32 v67, v110, v69, vcc
	v_cmp_lt_i32_e32 vcc, -1, v63
	v_and_b32_e32 v62, 0xffffff00, v62
	v_add_u32_e32 v78, 0xfd, v59
	v_cndmask_b32_e64 v59, v101, -1, vcc
	v_sub_u32_e32 v62, v62, v3
	v_bitop3_b32 v69, v59, v63, s43 bitop3:0x78
	v_add_u32_e32 v80, 0xfc, v62
	v_pk_add_f32 v[62:63], v[64:65], v[68:69] op_sel_hi:[0,1]
	v_not_b32_e32 v59, v63
	v_or_b32_e32 v64, 0x80000000, v63
	v_cmp_gt_i32_e32 vcc, 0, v63
	v_and_b32_e32 v67, 0xffffff00, v67
	v_and_b32_e32 v66, 0xffffff00, v66
	v_cndmask_b32_e32 v59, v64, v59, vcc
	v_and_b32_e32 v59, 0xffffff00, v59
	v_bitop3_b32 v63, v0, s44, v59 bitop3:0x36
	v_not_b32_e32 v59, v62
	v_or_b32_e32 v64, 0x80000000, v62
	v_cmp_gt_i32_e32 vcc, 0, v62
	v_and_b32_e32 v61, 0xffffff00, v61
	v_sub_u32_e32 v66, v66, v1
	v_sub_u32_e32 v67, v67, v0
	v_cndmask_b32_e32 v59, v64, v59, vcc
	v_sub_u32_e32 v61, v61, v56
	v_add_u32_e32 v67, 0xff, v67
	v_add_u32_e32 v66, 0xfe, v66
	v_and_b32_e32 v59, 0xffffff00, v59
	v_add_u32_e32 v61, 0xbf, v61
	v_bitop3_b32 v62, v0, 63, v59 bitop3:0x36
	v_max_u32_e32 v59, v66, v80
	v_max_u32_e32 v64, v67, v78
	v_max_u32_e32 v65, v104, v105
	v_max_u32_e32 v107, v73, v74
	v_max3_u32 v59, v64, v59, v63
	v_max_u32_e32 v64, v62, v61
	v_max_u32_e32 v68, v102, v103
	v_max_u32_e32 v69, v79, v81
	v_max3_u32 v65, v77, v106, v65
	v_max3_u32 v107, v75, v76, v107
	v_max_u32_e32 v108, v70, v72
	v_max3_u32 v59, v59, v64, v65
	v_max3_u32 v64, v68, v69, v107
	v_max3_u32 v59, v59, v64, v108
	s_nop 1
	v_mov_b32_dpp v64, v59 quad_perm:[1,0,3,2] row_mask:0xf bank_mask:0xf
	s_and_b32 s24, s40, 0x70
	s_lshl_b32 s24, s24, 2
	s_waitcnt lgkmcnt(0)
	v_max_u32_e32 v59, v59, v64
	s_nop 1
	v_max_u32_dpp v59, v59, v59 quad_perm:[2,3,0,1] row_mask:0xf bank_mask:0xf
	s_waitcnt lgkmcnt(0)
	v_cmp_ne_u32_e64 s[60:61], v67, v59
	v_cmp_ne_u32_e64 s[62:63], v66, v59
	v_cmp_ne_u32_e64 s[64:65], v78, v59
	v_cndmask_b32_e64 v64, 0, v67, s[60:61]
	v_cmp_ne_u32_e64 s[60:61], v80, v59
	v_cndmask_b32_e64 v65, 0, v66, s[62:63]
	v_cmp_ne_u32_e64 s[62:63], v72, v59
	v_cndmask_b32_e64 v66, 0, v78, s[64:65]
	v_cmp_ne_u32_e64 s[64:65], v70, v59
	v_cndmask_b32_e64 v67, 0, v80, s[60:61]
	v_cmp_ne_u32_e64 s[60:61], v74, v59
	v_cndmask_b32_e64 v68, 0, v72, s[62:63]
	v_cmp_ne_u32_e64 s[62:63], v73, v59
	v_cndmask_b32_e64 v69, 0, v70, s[64:65]
	v_cmp_ne_u32_e64 s[64:65], v76, v59
	v_cndmask_b32_e64 v70, 0, v74, s[60:61]
	v_cmp_ne_u32_e64 s[60:61], v75, v59
	v_cndmask_b32_e64 v72, 0, v73, s[62:63]
	v_cmp_ne_u32_e64 s[62:63], v81, v59
	v_cndmask_b32_e64 v73, 0, v76, s[64:65]
	v_cmp_ne_u32_e64 s[64:65], v79, v59
	v_cndmask_b32_e64 v74, 0, v75, s[60:61]
	v_cmp_ne_u32_e64 s[60:61], v103, v59
	v_cndmask_b32_e64 v75, 0, v81, s[62:63]
	v_cmp_ne_u32_e64 s[62:63], v102, v59
	v_cndmask_b32_e64 v76, 0, v79, s[64:65]
	v_cmp_ne_u32_e64 s[64:65], v105, v59
	v_cndmask_b32_e64 v78, 0, v103, s[60:61]
	v_cmp_ne_u32_e64 s[60:61], v104, v59
	v_cndmask_b32_e64 v79, 0, v102, s[62:63]
	v_cmp_ne_u32_e64 s[62:63], v61, v59
	v_cndmask_b32_e64 v80, 0, v105, s[64:65]
	v_cndmask_b32_e64 v81, 0, v104, s[60:61]
	v_cndmask_b32_e64 v102, 0, v61, s[62:63]
	v_max3_u32 v61, v64, v65, v66
	v_max3_u32 v61, v61, v67, v68
	v_max3_u32 v61, v61, v69, v70
	v_max3_u32 v61, v61, v72, v73
	v_cmp_ne_u32_e32 vcc, v77, v59
	v_max3_u32 v61, v61, v74, v75
	v_max3_u32 v61, v61, v76, v78
	v_cndmask_b32_e32 v77, 0, v77, vcc
	v_cmp_ne_u32_e32 vcc, v106, v59
	v_max3_u32 v61, v61, v79, v80
	v_max3_u32 v61, v61, v81, v102
	v_cndmask_b32_e32 v103, 0, v106, vcc
	v_cmp_ne_u32_e32 vcc, v63, v59
	v_max3_u32 v61, v61, v77, v103
	s_nop 0
	v_cndmask_b32_e32 v63, 0, v63, vcc
	v_cmp_ne_u32_e32 vcc, v62, v59
	s_nop 1
	v_cndmask_b32_e32 v62, 0, v62, vcc
	v_max3_u32 v61, v61, v63, v62
	s_nop 1
	v_max_u32_dpp v61, v61, v61 quad_perm:[1,0,3,2] row_mask:0xf bank_mask:0xf
	s_waitcnt lgkmcnt(0)
	s_nop 1
	v_max_u32_dpp v61, v61, v61 quad_perm:[2,3,0,1] row_mask:0xf bank_mask:0xf
	s_waitcnt lgkmcnt(0)
	v_cmp_ne_u32_e64 s[60:61], v64, v61
	v_cmp_ne_u32_e64 s[62:63], v65, v61
	v_cmp_ne_u32_e64 s[64:65], v66, v61
	v_cndmask_b32_e64 v64, 0, v64, s[60:61]
	v_cmp_ne_u32_e64 s[60:61], v67, v61
	v_cndmask_b32_e64 v65, 0, v65, s[62:63]
	v_cmp_ne_u32_e64 s[62:63], v68, v61
	v_cndmask_b32_e64 v66, 0, v66, s[64:65]
	v_cmp_ne_u32_e64 s[64:65], v69, v61
	v_cndmask_b32_e64 v67, 0, v67, s[60:61]
	v_cmp_ne_u32_e64 s[60:61], v70, v61
	v_cndmask_b32_e64 v68, 0, v68, s[62:63]
	v_cmp_ne_u32_e64 s[62:63], v72, v61
	v_cndmask_b32_e64 v69, 0, v69, s[64:65]
	v_cmp_ne_u32_e64 s[64:65], v73, v61
	v_cndmask_b32_e64 v70, 0, v70, s[60:61]
	v_cmp_ne_u32_e64 s[60:61], v74, v61
	v_cndmask_b32_e64 v72, 0, v72, s[62:63]
	v_cmp_ne_u32_e64 s[62:63], v75, v61
	v_cndmask_b32_e64 v73, 0, v73, s[64:65]
	v_cmp_ne_u32_e64 s[64:65], v76, v61
	v_cndmask_b32_e64 v74, 0, v74, s[60:61]
	v_cmp_ne_u32_e64 s[60:61], v78, v61
	v_cndmask_b32_e64 v75, 0, v75, s[62:63]
	v_cmp_ne_u32_e64 s[62:63], v79, v61
	v_cndmask_b32_e64 v76, 0, v76, s[64:65]
	v_cmp_ne_u32_e64 s[64:65], v80, v61
	v_cndmask_b32_e64 v78, 0, v78, s[60:61]
	v_cmp_ne_u32_e64 s[60:61], v81, v61
	v_cndmask_b32_e64 v79, 0, v79, s[62:63]
	v_cmp_ne_u32_e64 s[62:63], v102, v61
	v_cndmask_b32_e64 v80, 0, v80, s[64:65]
	v_cndmask_b32_e64 v81, 0, v81, s[60:61]
	v_cndmask_b32_e64 v104, 0, v102, s[62:63]
	v_max3_u32 v102, v64, v65, v66
	v_max3_u32 v102, v102, v67, v68
	v_max3_u32 v102, v102, v69, v70
	v_max3_u32 v102, v102, v72, v73
	v_cmp_ne_u32_e32 vcc, v77, v61
	v_max3_u32 v102, v102, v74, v75
	v_max3_u32 v102, v102, v76, v78
	v_cndmask_b32_e32 v77, 0, v77, vcc
	v_cmp_ne_u32_e32 vcc, v103, v61
	v_max3_u32 v102, v102, v79, v80
	v_max3_u32 v102, v102, v81, v104
	v_cndmask_b32_e32 v103, 0, v103, vcc
	v_cmp_ne_u32_e32 vcc, v63, v61
	v_max3_u32 v102, v102, v77, v103
	s_nop 0
	v_cndmask_b32_e32 v63, 0, v63, vcc
	v_cmp_ne_u32_e32 vcc, v62, v61
	s_nop 1
	v_cndmask_b32_e32 v62, 0, v62, vcc
	v_max3_u32 v102, v102, v63, v62
	s_nop 1
	v_max_u32_dpp v102, v102, v102 quad_perm:[1,0,3,2] row_mask:0xf bank_mask:0xf
	s_waitcnt lgkmcnt(0)
	s_nop 1
	v_max_u32_dpp v102, v102, v102 quad_perm:[2,3,0,1] row_mask:0xf bank_mask:0xf
	s_waitcnt lgkmcnt(0)
	v_cmp_ne_u32_e64 s[60:61], v64, v102
	v_cmp_ne_u32_e64 s[62:63], v65, v102
	v_cmp_ne_u32_e64 s[64:65], v66, v102
	v_cndmask_b32_e64 v64, 0, v64, s[60:61]
	v_cmp_ne_u32_e64 s[60:61], v67, v102
	v_cndmask_b32_e64 v65, 0, v65, s[62:63]
	v_cmp_ne_u32_e64 s[62:63], v68, v102
	v_cndmask_b32_e64 v66, 0, v66, s[64:65]
	v_cmp_ne_u32_e64 s[64:65], v69, v102
	v_cndmask_b32_e64 v67, 0, v67, s[60:61]
	v_cmp_ne_u32_e64 s[60:61], v70, v102
	v_cndmask_b32_e64 v68, 0, v68, s[62:63]
	v_cmp_ne_u32_e64 s[62:63], v72, v102
	v_cndmask_b32_e64 v69, 0, v69, s[64:65]
	v_cmp_ne_u32_e64 s[64:65], v73, v102
	v_cndmask_b32_e64 v70, 0, v70, s[60:61]
	v_cmp_ne_u32_e64 s[60:61], v74, v102
	v_cndmask_b32_e64 v72, 0, v72, s[62:63]
	v_cmp_ne_u32_e64 s[62:63], v75, v102
	v_cndmask_b32_e64 v73, 0, v73, s[64:65]
	v_cmp_ne_u32_e64 s[64:65], v76, v102
	v_cndmask_b32_e64 v74, 0, v74, s[60:61]
	v_cmp_ne_u32_e64 s[60:61], v78, v102
	v_cndmask_b32_e64 v75, 0, v75, s[62:63]
	v_cmp_ne_u32_e64 s[62:63], v79, v102
	v_cndmask_b32_e64 v76, 0, v76, s[64:65]
	v_cmp_ne_u32_e64 s[64:65], v80, v102
	v_cndmask_b32_e64 v78, 0, v78, s[60:61]
	v_cmp_ne_u32_e64 s[60:61], v81, v102
	v_cndmask_b32_e64 v79, 0, v79, s[62:63]
	v_cmp_ne_u32_e64 s[62:63], v104, v102
	v_cndmask_b32_e64 v80, 0, v80, s[64:65]
	v_cmp_ne_u32_e64 s[64:65], v77, v102
	v_cndmask_b32_e64 v81, 0, v81, s[60:61]
	v_cmp_ne_u32_e64 s[60:61], v103, v102
	v_cndmask_b32_e64 v104, 0, v104, s[62:63]
	v_cndmask_b32_e64 v77, 0, v77, s[64:65]
	v_cndmask_b32_e64 v105, 0, v103, s[60:61]
	v_max3_u32 v103, v64, v65, v66
	v_max3_u32 v103, v103, v67, v68
	v_max3_u32 v103, v103, v69, v70
	v_max3_u32 v103, v103, v72, v73
	v_max3_u32 v103, v103, v74, v75
	v_max3_u32 v103, v103, v76, v78
	v_cmp_ne_u32_e32 vcc, v63, v102
	v_max3_u32 v103, v103, v79, v80
	v_max3_u32 v103, v103, v81, v104
	v_cndmask_b32_e32 v63, 0, v63, vcc
	v_cmp_ne_u32_e32 vcc, v62, v102
	v_max3_u32 v103, v103, v77, v105
	s_nop 0
	v_cndmask_b32_e32 v62, 0, v62, vcc
	v_max3_u32 v103, v103, v63, v62
	s_nop 1
	v_max_u32_dpp v103, v103, v103 quad_perm:[1,0,3,2] row_mask:0xf bank_mask:0xf
	s_waitcnt lgkmcnt(0)
	s_nop 1
	v_max_u32_dpp v103, v103, v103 quad_perm:[2,3,0,1] row_mask:0xf bank_mask:0xf
	s_waitcnt lgkmcnt(0)
	v_cmp_ne_u32_e64 s[60:61], v64, v103
	v_cmp_ne_u32_e64 s[62:63], v65, v103
	v_cmp_ne_u32_e64 s[64:65], v66, v103
	v_cndmask_b32_e64 v64, 0, v64, s[60:61]
	v_cmp_ne_u32_e64 s[60:61], v67, v103
	v_cndmask_b32_e64 v65, 0, v65, s[62:63]
	v_cmp_ne_u32_e64 s[62:63], v68, v103
	v_cndmask_b32_e64 v66, 0, v66, s[64:65]
	v_cmp_ne_u32_e64 s[64:65], v69, v103
	v_cndmask_b32_e64 v67, 0, v67, s[60:61]
	v_cmp_ne_u32_e64 s[60:61], v70, v103
	v_cndmask_b32_e64 v68, 0, v68, s[62:63]
	v_cmp_ne_u32_e64 s[62:63], v72, v103
	v_cndmask_b32_e64 v69, 0, v69, s[64:65]
	v_cmp_ne_u32_e64 s[64:65], v73, v103
	v_cndmask_b32_e64 v70, 0, v70, s[60:61]
	v_cmp_ne_u32_e64 s[60:61], v74, v103
	v_cndmask_b32_e64 v72, 0, v72, s[62:63]
	v_cmp_ne_u32_e64 s[62:63], v75, v103
	v_cndmask_b32_e64 v73, 0, v73, s[64:65]
	v_cmp_ne_u32_e64 s[64:65], v76, v103
	v_cndmask_b32_e64 v74, 0, v74, s[60:61]
	v_cndmask_b32_e64 v75, 0, v75, s[62:63]
	v_cndmask_b32_e64 v106, 0, v76, s[64:65]
	v_cmp_ne_u32_e32 vcc, v78, v103
	v_max3_u32 v76, v64, v65, v66
	v_max3_u32 v76, v76, v67, v68
	v_cndmask_b32_e32 v78, 0, v78, vcc
	v_cmp_ne_u32_e32 vcc, v79, v103
	v_max3_u32 v76, v76, v69, v70
	v_max3_u32 v76, v76, v72, v73
	v_cndmask_b32_e32 v79, 0, v79, vcc
	v_cmp_ne_u32_e32 vcc, v80, v103
	v_max3_u32 v76, v76, v74, v75
	v_max3_u32 v76, v76, v106, v78
	v_cndmask_b32_e32 v80, 0, v80, vcc
	v_cmp_ne_u32_e32 vcc, v81, v103
	v_max3_u32 v76, v76, v79, v80
	s_nop 0
	v_cndmask_b32_e32 v81, 0, v81, vcc
	v_cmp_ne_u32_e32 vcc, v104, v103
	s_nop 1
	v_cndmask_b32_e32 v104, 0, v104, vcc
	v_cmp_ne_u32_e32 vcc, v77, v103
	v_max3_u32 v76, v76, v81, v104
	s_nop 0
	v_cndmask_b32_e32 v77, 0, v77, vcc
	v_cmp_ne_u32_e32 vcc, v105, v103
	s_nop 1
	v_cndmask_b32_e32 v105, 0, v105, vcc
	v_cmp_ne_u32_e32 vcc, v63, v103
	v_max3_u32 v76, v76, v77, v105
	s_nop 0
	v_cndmask_b32_e32 v63, 0, v63, vcc
	v_cmp_ne_u32_e32 vcc, v62, v103
	s_nop 1
	v_cndmask_b32_e32 v62, 0, v62, vcc
	v_max3_u32 v76, v76, v63, v62
	s_nop 1
	v_max_u32_dpp v76, v76, v76 quad_perm:[1,0,3,2] row_mask:0xf bank_mask:0xf
	s_waitcnt lgkmcnt(0)
	s_nop 1
	v_max_u32_dpp v76, v76, v76 quad_perm:[2,3,0,1] row_mask:0xf bank_mask:0xf
	s_waitcnt lgkmcnt(0)
	v_cmp_ne_u32_e64 s[60:61], v64, v76
	v_cmp_ne_u32_e64 s[62:63], v65, v76
	v_cmp_ne_u32_e64 s[64:65], v66, v76
	v_cndmask_b32_e64 v64, 0, v64, s[60:61]
	v_cmp_ne_u32_e64 s[60:61], v67, v76
	v_cndmask_b32_e64 v65, 0, v65, s[62:63]
	v_cmp_ne_u32_e64 s[62:63], v68, v76
	v_cndmask_b32_e64 v66, 0, v66, s[64:65]
	v_cmp_ne_u32_e64 s[64:65], v69, v76
	v_cndmask_b32_e64 v67, 0, v67, s[60:61]
	v_cmp_ne_u32_e64 s[60:61], v70, v76
	v_cndmask_b32_e64 v68, 0, v68, s[62:63]
	v_cmp_ne_u32_e64 s[62:63], v72, v76
	v_cndmask_b32_e64 v69, 0, v69, s[64:65]
	v_cmp_ne_u32_e64 s[64:65], v73, v76
	v_cndmask_b32_e64 v70, 0, v70, s[60:61]
	v_cmp_ne_u32_e64 s[60:61], v74, v76
	v_cndmask_b32_e64 v72, 0, v72, s[62:63]
	v_cmp_ne_u32_e64 s[62:63], v75, v76
	v_cndmask_b32_e64 v73, 0, v73, s[64:65]
	v_cmp_ne_u32_e64 s[64:65], v106, v76
	v_cndmask_b32_e64 v74, 0, v74, s[60:61]
	v_cmp_ne_u32_e64 s[60:61], v78, v76
	v_cndmask_b32_e64 v75, 0, v75, s[62:63]
	v_cmp_ne_u32_e64 s[62:63], v79, v76
	v_cndmask_b32_e64 v106, 0, v106, s[64:65]
	v_cmp_ne_u32_e64 s[64:65], v80, v76
	v_cndmask_b32_e64 v78, 0, v78, s[60:61]
	v_cmp_ne_u32_e64 s[60:61], v81, v76
	v_cndmask_b32_e64 v79, 0, v79, s[62:63]
	v_cmp_ne_u32_e64 s[62:63], v104, v76
	v_cndmask_b32_e64 v80, 0, v80, s[64:65]
	v_cmp_ne_u32_e64 s[64:65], v77, v76
	v_cndmask_b32_e64 v81, 0, v81, s[60:61]
	v_cndmask_b32_e64 v104, 0, v104, s[62:63]
	v_cndmask_b32_e64 v107, 0, v77, s[64:65]
	v_max3_u32 v77, v64, v65, v66
	v_max3_u32 v77, v77, v67, v68
	v_max3_u32 v77, v77, v69, v70
	v_max3_u32 v77, v77, v72, v73
	v_max3_u32 v77, v77, v74, v75
	v_cmp_ne_u32_e32 vcc, v105, v76
	v_max3_u32 v77, v77, v106, v78
	v_max3_u32 v77, v77, v79, v80
	v_cndmask_b32_e32 v105, 0, v105, vcc
	v_cmp_ne_u32_e32 vcc, v63, v76
	v_max3_u32 v77, v77, v81, v104
	v_max3_u32 v77, v77, v107, v105
	v_cndmask_b32_e32 v63, 0, v63, vcc
	v_cmp_ne_u32_e32 vcc, v62, v76
	s_nop 1
	v_cndmask_b32_e32 v62, 0, v62, vcc
	v_max3_u32 v77, v77, v63, v62
	s_nop 1
	v_max_u32_dpp v77, v77, v77 quad_perm:[1,0,3,2] row_mask:0xf bank_mask:0xf
	s_waitcnt lgkmcnt(0)
	s_nop 1
	v_max_u32_dpp v77, v77, v77 quad_perm:[2,3,0,1] row_mask:0xf bank_mask:0xf
	s_waitcnt lgkmcnt(0)
	v_cmp_ne_u32_e64 s[60:61], v64, v77
	v_cmp_ne_u32_e64 s[62:63], v65, v77
	v_cmp_ne_u32_e64 s[64:65], v66, v77
	v_cndmask_b32_e64 v64, 0, v64, s[60:61]
	v_cmp_ne_u32_e64 s[60:61], v67, v77
	v_cndmask_b32_e64 v65, 0, v65, s[62:63]
	v_cmp_ne_u32_e64 s[62:63], v68, v77
	v_cndmask_b32_e64 v66, 0, v66, s[64:65]
	v_cmp_ne_u32_e64 s[64:65], v69, v77
	v_cndmask_b32_e64 v67, 0, v67, s[60:61]
	v_cmp_ne_u32_e64 s[60:61], v70, v77
	v_cndmask_b32_e64 v68, 0, v68, s[62:63]
	v_cmp_ne_u32_e64 s[62:63], v72, v77
	v_cndmask_b32_e64 v69, 0, v69, s[64:65]
	v_cmp_ne_u32_e64 s[64:65], v73, v77
	v_cndmask_b32_e64 v70, 0, v70, s[60:61]
	v_cmp_ne_u32_e64 s[60:61], v74, v77
	v_cndmask_b32_e64 v72, 0, v72, s[62:63]
	v_cmp_ne_u32_e64 s[62:63], v75, v77
	v_cndmask_b32_e64 v73, 0, v73, s[64:65]
	v_cmp_ne_u32_e64 s[64:65], v106, v77
	v_cndmask_b32_e64 v74, 0, v74, s[60:61]
	v_cmp_ne_u32_e64 s[60:61], v78, v77
	v_cndmask_b32_e64 v75, 0, v75, s[62:63]
	v_cndmask_b32_e64 v106, 0, v106, s[64:65]
	v_cndmask_b32_e64 v108, 0, v78, s[60:61]
	v_cmp_ne_u32_e32 vcc, v79, v77
	v_max3_u32 v78, v64, v65, v66
	v_max3_u32 v78, v78, v67, v68
	v_cndmask_b32_e32 v79, 0, v79, vcc
	v_cmp_ne_u32_e32 vcc, v80, v77
	v_max3_u32 v78, v78, v69, v70
	v_max3_u32 v78, v78, v72, v73
	v_cndmask_b32_e32 v80, 0, v80, vcc
	v_cmp_ne_u32_e32 vcc, v81, v77
	v_max3_u32 v78, v78, v74, v75
	v_max3_u32 v78, v78, v106, v108
	v_cndmask_b32_e32 v81, 0, v81, vcc
	v_cmp_ne_u32_e32 vcc, v104, v77
	v_max3_u32 v78, v78, v79, v80
	s_nop 0
	v_cndmask_b32_e32 v104, 0, v104, vcc
	v_cmp_ne_u32_e32 vcc, v107, v77
	v_max3_u32 v78, v78, v81, v104
	s_nop 0
	v_cndmask_b32_e32 v107, 0, v107, vcc
	v_cmp_ne_u32_e32 vcc, v105, v77
	s_nop 1
	v_cndmask_b32_e32 v105, 0, v105, vcc
	v_cmp_ne_u32_e32 vcc, v63, v77
	v_max3_u32 v78, v78, v107, v105
	s_nop 0
	v_cndmask_b32_e32 v63, 0, v63, vcc
	v_cmp_ne_u32_e32 vcc, v62, v77
	s_nop 1
	v_cndmask_b32_e32 v62, 0, v62, vcc
	v_max3_u32 v78, v78, v63, v62
	s_nop 1
	v_max_u32_dpp v78, v78, v78 quad_perm:[1,0,3,2] row_mask:0xf bank_mask:0xf
	s_waitcnt lgkmcnt(0)
	s_nop 1
	v_max_u32_dpp v78, v78, v78 quad_perm:[2,3,0,1] row_mask:0xf bank_mask:0xf
	s_waitcnt lgkmcnt(0)
	v_cmp_ne_u32_e64 s[60:61], v64, v78
	v_cmp_ne_u32_e64 s[62:63], v65, v78
	v_cmp_ne_u32_e64 s[64:65], v66, v78
	v_cndmask_b32_e64 v64, 0, v64, s[60:61]
	v_cmp_ne_u32_e64 s[60:61], v67, v78
	v_cndmask_b32_e64 v65, 0, v65, s[62:63]
	v_cmp_ne_u32_e64 s[62:63], v68, v78
	v_cndmask_b32_e64 v66, 0, v66, s[64:65]
	v_cmp_ne_u32_e64 s[64:65], v69, v78
	v_cndmask_b32_e64 v67, 0, v67, s[60:61]
	v_cmp_ne_u32_e64 s[60:61], v70, v78
	v_cndmask_b32_e64 v68, 0, v68, s[62:63]
	v_cmp_ne_u32_e64 s[62:63], v72, v78
	v_cndmask_b32_e64 v69, 0, v69, s[64:65]
	v_cmp_ne_u32_e64 s[64:65], v73, v78
	v_cndmask_b32_e64 v70, 0, v70, s[60:61]
	v_cmp_ne_u32_e64 s[60:61], v74, v78
	v_cndmask_b32_e64 v72, 0, v72, s[62:63]
	v_cmp_ne_u32_e64 s[62:63], v75, v78
	v_cndmask_b32_e64 v73, 0, v73, s[64:65]
	v_cmp_ne_u32_e64 s[64:65], v106, v78
	v_cndmask_b32_e64 v74, 0, v74, s[60:61]
	v_cmp_ne_u32_e64 s[60:61], v108, v78
	v_cndmask_b32_e64 v75, 0, v75, s[62:63]
	v_cmp_ne_u32_e64 s[62:63], v79, v78
	v_cndmask_b32_e64 v106, 0, v106, s[64:65]
	v_cndmask_b32_e64 v108, 0, v108, s[60:61]
	v_cndmask_b32_e64 v109, 0, v79, s[62:63]
	v_max3_u32 v79, v64, v65, v66
	v_cmp_ne_u32_e32 vcc, v80, v78
	v_max3_u32 v79, v79, v67, v68
	v_max3_u32 v79, v79, v69, v70
	v_cndmask_b32_e32 v80, 0, v80, vcc
	v_cmp_ne_u32_e32 vcc, v81, v78
	v_max3_u32 v79, v79, v72, v73
	v_max3_u32 v79, v79, v74, v75
	v_cndmask_b32_e32 v81, 0, v81, vcc
	v_cmp_ne_u32_e32 vcc, v104, v78
	v_max3_u32 v79, v79, v106, v108
	v_max3_u32 v79, v79, v109, v80
	v_cndmask_b32_e32 v104, 0, v104, vcc
	v_cmp_ne_u32_e32 vcc, v107, v78
	v_max3_u32 v79, v79, v81, v104
	s_nop 0
	v_cndmask_b32_e32 v107, 0, v107, vcc
	v_cmp_ne_u32_e32 vcc, v105, v78
	s_nop 1
	v_cndmask_b32_e32 v105, 0, v105, vcc
	v_cmp_ne_u32_e32 vcc, v63, v78
	v_max3_u32 v79, v79, v107, v105
	s_nop 0
	v_cndmask_b32_e32 v63, 0, v63, vcc
	v_cmp_ne_u32_e32 vcc, v62, v78
	s_nop 1
	v_cndmask_b32_e32 v62, 0, v62, vcc
	v_max3_u32 v79, v79, v63, v62
	s_nop 1
	v_max_u32_dpp v79, v79, v79 quad_perm:[1,0,3,2] row_mask:0xf bank_mask:0xf
	s_waitcnt lgkmcnt(0)
	s_nop 1
	v_max_u32_dpp v79, v79, v79 quad_perm:[2,3,0,1] row_mask:0xf bank_mask:0xf
	s_waitcnt lgkmcnt(0)
	v_cmp_ne_u32_e64 s[60:61], v64, v79
	v_cmp_ne_u32_e64 s[62:63], v65, v79
	v_cmp_ne_u32_e64 s[64:65], v66, v79
	v_cndmask_b32_e64 v64, 0, v64, s[60:61]
	v_cmp_ne_u32_e64 s[60:61], v67, v79
	v_cndmask_b32_e64 v65, 0, v65, s[62:63]
	v_cmp_ne_u32_e64 s[62:63], v68, v79
	v_cndmask_b32_e64 v66, 0, v66, s[64:65]
	v_cmp_ne_u32_e64 s[64:65], v69, v79
	v_cndmask_b32_e64 v67, 0, v67, s[60:61]
	v_cmp_ne_u32_e64 s[60:61], v70, v79
	v_cndmask_b32_e64 v68, 0, v68, s[62:63]
	v_cmp_ne_u32_e64 s[62:63], v72, v79
	v_cndmask_b32_e64 v69, 0, v69, s[64:65]
	v_cmp_ne_u32_e64 s[64:65], v73, v79
	v_cndmask_b32_e64 v70, 0, v70, s[60:61]
	v_cmp_ne_u32_e64 s[60:61], v74, v79
	v_cndmask_b32_e64 v72, 0, v72, s[62:63]
	v_cmp_ne_u32_e64 s[62:63], v75, v79
	v_cndmask_b32_e64 v73, 0, v73, s[64:65]
	v_cmp_ne_u32_e64 s[64:65], v106, v79
	v_cndmask_b32_e64 v74, 0, v74, s[60:61]
	v_cmp_ne_u32_e64 s[60:61], v108, v79
	v_cndmask_b32_e64 v75, 0, v75, s[62:63]
	v_cmp_ne_u32_e64 s[62:63], v109, v79
	v_cndmask_b32_e64 v106, 0, v106, s[64:65]
	v_cmp_ne_u32_e64 s[64:65], v80, v79
	v_cndmask_b32_e64 v108, 0, v108, s[60:61]
	v_cmp_ne_u32_e64 s[60:61], v81, v79
	v_cndmask_b32_e64 v109, 0, v109, s[62:63]
	v_cmp_ne_u32_e64 s[62:63], v104, v79
	v_cndmask_b32_e64 v80, 0, v80, s[64:65]
	v_cmp_ne_u32_e64 s[64:65], v107, v79
	v_cndmask_b32_e64 v81, 0, v81, s[60:61]
	v_cmp_ne_u32_e64 s[60:61], v105, v79
	v_cndmask_b32_e64 v104, 0, v104, s[62:63]
	v_cmp_ne_u32_e64 s[62:63], v63, v79
	v_cndmask_b32_e64 v107, 0, v107, s[64:65]
	v_cmp_ne_u32_e64 s[64:65], v62, v79
	v_cndmask_b32_e64 v105, 0, v105, s[60:61]
	v_cndmask_b32_e64 v63, 0, v63, s[62:63]
	v_cndmask_b32_e64 v110, 0, v62, s[64:65]
	v_max3_u32 v62, v64, v65, v66
	v_max3_u32 v62, v62, v67, v68
	v_max3_u32 v62, v62, v69, v70
	v_max3_u32 v62, v62, v72, v73
	v_max3_u32 v62, v62, v74, v75
	v_max3_u32 v62, v62, v106, v108
	v_max3_u32 v62, v62, v109, v80
	v_max3_u32 v62, v62, v81, v104
	v_max3_u32 v62, v62, v107, v105
	v_max3_u32 v62, v62, v63, v110
	s_nop 1
	v_max_u32_dpp v62, v62, v62 quad_perm:[1,0,3,2] row_mask:0xf bank_mask:0xf
	s_waitcnt lgkmcnt(0)
	s_nop 1
	v_max_u32_dpp v62, v62, v62 quad_perm:[2,3,0,1] row_mask:0xf bank_mask:0xf
	s_waitcnt lgkmcnt(0)
	v_cmp_ne_u32_e64 s[60:61], v64, v62
	v_cmp_ne_u32_e64 s[62:63], v65, v62
	v_cmp_ne_u32_e64 s[64:65], v66, v62
	v_cndmask_b32_e64 v64, 0, v64, s[60:61]
	v_cmp_ne_u32_e64 s[60:61], v67, v62
	v_cndmask_b32_e64 v65, 0, v65, s[62:63]
	v_cmp_ne_u32_e64 s[62:63], v68, v62
	v_cndmask_b32_e64 v66, 0, v66, s[64:65]
	v_cmp_ne_u32_e64 s[64:65], v69, v62
	v_cndmask_b32_e64 v67, 0, v67, s[60:61]
	v_cmp_ne_u32_e64 s[60:61], v70, v62
	v_cndmask_b32_e64 v68, 0, v68, s[62:63]
	v_cmp_ne_u32_e64 s[62:63], v72, v62
	v_cndmask_b32_e64 v69, 0, v69, s[64:65]
	v_cmp_ne_u32_e64 s[64:65], v73, v62
	v_cndmask_b32_e64 v70, 0, v70, s[60:61]
	v_cmp_ne_u32_e64 s[60:61], v74, v62
	v_cndmask_b32_e64 v72, 0, v72, s[62:63]
	v_cmp_ne_u32_e64 s[62:63], v75, v62
	v_cndmask_b32_e64 v73, 0, v73, s[64:65]
	v_cmp_ne_u32_e64 s[64:65], v106, v62
	v_cndmask_b32_e64 v74, 0, v74, s[60:61]
	v_cmp_ne_u32_e64 s[60:61], v108, v62
	v_cndmask_b32_e64 v75, 0, v75, s[62:63]
	v_cmp_ne_u32_e64 s[62:63], v109, v62
	v_cndmask_b32_e64 v106, 0, v106, s[64:65]
	v_cmp_ne_u32_e64 s[64:65], v80, v62
	v_cndmask_b32_e64 v108, 0, v108, s[60:61]
	v_cmp_ne_u32_e64 s[60:61], v81, v62
	v_cndmask_b32_e64 v109, 0, v109, s[62:63]
	v_cmp_ne_u32_e64 s[62:63], v104, v62
	v_cndmask_b32_e64 v80, 0, v80, s[64:65]
	v_cmp_ne_u32_e64 s[64:65], v107, v62
	v_cndmask_b32_e64 v81, 0, v81, s[60:61]
	v_cmp_ne_u32_e64 s[60:61], v105, v62
	v_cndmask_b32_e64 v104, 0, v104, s[62:63]
	v_cmp_ne_u32_e64 s[62:63], v63, v62
	v_cndmask_b32_e64 v107, 0, v107, s[64:65]
	v_cndmask_b32_e64 v105, 0, v105, s[60:61]
	v_cndmask_b32_e64 v111, 0, v63, s[62:63]
	v_max3_u32 v63, v64, v65, v66
	v_max3_u32 v63, v63, v67, v68
	v_max3_u32 v63, v63, v69, v70
	v_max3_u32 v63, v63, v72, v73
	v_max3_u32 v63, v63, v74, v75
	v_max3_u32 v63, v63, v106, v108
	v_max3_u32 v63, v63, v109, v80
	v_cmp_ne_u32_e32 vcc, v110, v62
	v_max3_u32 v63, v63, v81, v104
	v_max3_u32 v63, v63, v107, v105
	v_cndmask_b32_e32 v110, 0, v110, vcc
	v_max3_u32 v63, v63, v111, v110
	s_nop 1
	v_max_u32_dpp v63, v63, v63 quad_perm:[1,0,3,2] row_mask:0xf bank_mask:0xf
	s_waitcnt lgkmcnt(0)
	s_nop 1
	v_max_u32_dpp v63, v63, v63 quad_perm:[2,3,0,1] row_mask:0xf bank_mask:0xf
	s_waitcnt lgkmcnt(0)
	v_cmp_ne_u32_e64 s[60:61], v64, v63
	v_cmp_ne_u32_e64 s[62:63], v65, v63
	v_cmp_ne_u32_e64 s[64:65], v66, v63
	v_cndmask_b32_e64 v112, 0, v64, s[60:61]
	v_cndmask_b32_e64 v65, 0, v65, s[62:63]
	v_cndmask_b32_e64 v66, 0, v66, s[64:65]
	v_cmp_ne_u32_e32 vcc, v67, v63
	v_max3_u32 v64, v112, v65, v66
	s_nop 0
	v_cndmask_b32_e32 v67, 0, v67, vcc
	v_cmp_ne_u32_e32 vcc, v68, v63
	s_nop 1
	v_cndmask_b32_e32 v68, 0, v68, vcc
	v_cmp_ne_u32_e32 vcc, v69, v63
	v_max3_u32 v64, v64, v67, v68
	s_nop 0
	v_cndmask_b32_e32 v69, 0, v69, vcc
	v_cmp_ne_u32_e32 vcc, v70, v63
	s_nop 1
	v_cndmask_b32_e32 v70, 0, v70, vcc
	v_cmp_ne_u32_e32 vcc, v72, v63
	v_max3_u32 v64, v64, v69, v70
	s_nop 0
	v_cndmask_b32_e32 v72, 0, v72, vcc
	v_cmp_ne_u32_e32 vcc, v73, v63
	s_nop 1
	v_cndmask_b32_e32 v73, 0, v73, vcc
	v_cmp_ne_u32_e32 vcc, v74, v63
	v_max3_u32 v64, v64, v72, v73
	s_nop 0
	v_cndmask_b32_e32 v74, 0, v74, vcc
	v_cmp_ne_u32_e32 vcc, v75, v63
	s_nop 1
	v_cndmask_b32_e32 v75, 0, v75, vcc
	v_cmp_ne_u32_e32 vcc, v106, v63
	v_max3_u32 v64, v64, v74, v75
	s_nop 0
	v_cndmask_b32_e32 v106, 0, v106, vcc
	v_cmp_ne_u32_e32 vcc, v108, v63
	s_nop 1
	v_cndmask_b32_e32 v108, 0, v108, vcc
	v_cmp_ne_u32_e32 vcc, v109, v63
	v_max3_u32 v64, v64, v106, v108
	s_nop 0
	v_cndmask_b32_e32 v109, 0, v109, vcc
	v_cmp_ne_u32_e32 vcc, v80, v63
	s_nop 1
	v_cndmask_b32_e32 v80, 0, v80, vcc
	v_cmp_ne_u32_e32 vcc, v81, v63
	v_max3_u32 v64, v64, v109, v80
	s_nop 0
	v_cndmask_b32_e32 v81, 0, v81, vcc
	v_cmp_ne_u32_e32 vcc, v104, v63
	s_nop 1
	v_cndmask_b32_e32 v104, 0, v104, vcc
	v_cmp_ne_u32_e32 vcc, v107, v63
	v_max3_u32 v64, v64, v81, v104
	s_nop 0
	v_cndmask_b32_e32 v107, 0, v107, vcc
	v_cmp_ne_u32_e32 vcc, v105, v63
	s_nop 1
	v_cndmask_b32_e32 v105, 0, v105, vcc
	v_cmp_ne_u32_e32 vcc, v111, v63
	v_max3_u32 v64, v64, v107, v105
	s_nop 0
	v_cndmask_b32_e32 v111, 0, v111, vcc
	v_cmp_ne_u32_e32 vcc, v110, v63
	s_nop 1
	v_cndmask_b32_e32 v110, 0, v110, vcc
	v_max3_u32 v64, v64, v111, v110
	s_nop 1
	v_max_u32_dpp v64, v64, v64 quad_perm:[1,0,3,2] row_mask:0xf bank_mask:0xf
	s_waitcnt lgkmcnt(0)
	s_nop 1
	v_max_u32_dpp v64, v64, v64 quad_perm:[2,3,0,1] row_mask:0xf bank_mask:0xf
	s_waitcnt lgkmcnt(0)
	v_cmp_ne_u32_e64 s[60:61], v112, v64
	v_cmp_ne_u32_e64 s[62:63], v65, v64
	v_cmp_ne_u32_e64 s[64:65], v66, v64
	v_cndmask_b32_e64 v112, 0, v112, s[60:61]
	v_cndmask_b32_e64 v113, 0, v65, s[62:63]
	v_cndmask_b32_e64 v66, 0, v66, s[64:65]
	v_cmp_ne_u32_e32 vcc, v67, v64
	v_max3_u32 v65, v112, v113, v66
	s_nop 0
	v_cndmask_b32_e32 v67, 0, v67, vcc
	v_cmp_ne_u32_e32 vcc, v68, v64
	s_nop 1
	v_cndmask_b32_e32 v68, 0, v68, vcc
	v_cmp_ne_u32_e32 vcc, v69, v64
	v_max3_u32 v65, v65, v67, v68
	s_nop 0
	v_cndmask_b32_e32 v69, 0, v69, vcc
	v_cmp_ne_u32_e32 vcc, v70, v64
	s_nop 1
	v_cndmask_b32_e32 v70, 0, v70, vcc
	v_cmp_ne_u32_e32 vcc, v72, v64
	v_max3_u32 v65, v65, v69, v70
	s_nop 0
	v_cndmask_b32_e32 v72, 0, v72, vcc
	v_cmp_ne_u32_e32 vcc, v73, v64
	s_nop 1
	v_cndmask_b32_e32 v73, 0, v73, vcc
	v_cmp_ne_u32_e32 vcc, v74, v64
	v_max3_u32 v65, v65, v72, v73
	s_nop 0
	v_cndmask_b32_e32 v74, 0, v74, vcc
	v_cmp_ne_u32_e32 vcc, v75, v64
	s_nop 1
	v_cndmask_b32_e32 v75, 0, v75, vcc
	v_cmp_ne_u32_e32 vcc, v106, v64
	v_max3_u32 v65, v65, v74, v75
	s_nop 0
	v_cndmask_b32_e32 v106, 0, v106, vcc
	v_cmp_ne_u32_e32 vcc, v108, v64
	s_nop 1
	v_cndmask_b32_e32 v108, 0, v108, vcc
	v_cmp_ne_u32_e32 vcc, v109, v64
	v_max3_u32 v65, v65, v106, v108
	s_nop 0
	v_cndmask_b32_e32 v109, 0, v109, vcc
	v_cmp_ne_u32_e32 vcc, v80, v64
	s_nop 1
	v_cndmask_b32_e32 v80, 0, v80, vcc
	v_cmp_ne_u32_e32 vcc, v81, v64
	v_max3_u32 v65, v65, v109, v80
	s_nop 0
	v_cndmask_b32_e32 v81, 0, v81, vcc
	v_cmp_ne_u32_e32 vcc, v104, v64
	s_nop 1
	v_cndmask_b32_e32 v104, 0, v104, vcc
	v_cmp_ne_u32_e32 vcc, v107, v64
	v_max3_u32 v65, v65, v81, v104
	s_nop 0
	v_cndmask_b32_e32 v107, 0, v107, vcc
	v_cmp_ne_u32_e32 vcc, v105, v64
	s_nop 1
	v_cndmask_b32_e32 v105, 0, v105, vcc
	v_cmp_ne_u32_e32 vcc, v111, v64
	v_max3_u32 v65, v65, v107, v105
	s_nop 0
	v_cndmask_b32_e32 v111, 0, v111, vcc
	v_cmp_ne_u32_e32 vcc, v110, v64
	s_nop 1
	v_cndmask_b32_e32 v110, 0, v110, vcc
	v_max3_u32 v65, v65, v111, v110
	s_nop 1
	v_max_u32_dpp v65, v65, v65 quad_perm:[1,0,3,2] row_mask:0xf bank_mask:0xf
	s_waitcnt lgkmcnt(0)
	s_nop 1
	v_max_u32_dpp v65, v65, v65 quad_perm:[2,3,0,1] row_mask:0xf bank_mask:0xf
	s_waitcnt lgkmcnt(0)
	v_cmp_ne_u32_e64 s[60:61], v112, v65
	v_cmp_ne_u32_e64 s[62:63], v113, v65
	v_cmp_ne_u32_e64 s[64:65], v66, v65
	v_cndmask_b32_e64 v112, 0, v112, s[60:61]
	v_cndmask_b32_e64 v113, 0, v113, s[62:63]
	v_cndmask_b32_e64 v114, 0, v66, s[64:65]
	v_cmp_ne_u32_e32 vcc, v67, v65
	v_max3_u32 v66, v112, v113, v114
	s_nop 0
	v_cndmask_b32_e32 v67, 0, v67, vcc
	v_cmp_ne_u32_e32 vcc, v68, v65
	s_nop 1
	v_cndmask_b32_e32 v68, 0, v68, vcc
	v_cmp_ne_u32_e32 vcc, v69, v65
	v_max3_u32 v66, v66, v67, v68
	s_nop 0
	v_cndmask_b32_e32 v69, 0, v69, vcc
	v_cmp_ne_u32_e32 vcc, v70, v65
	s_nop 1
	v_cndmask_b32_e32 v70, 0, v70, vcc
	v_cmp_ne_u32_e32 vcc, v72, v65
	v_max3_u32 v66, v66, v69, v70
	s_nop 0
	v_cndmask_b32_e32 v72, 0, v72, vcc
	v_cmp_ne_u32_e32 vcc, v73, v65
	s_nop 1
	v_cndmask_b32_e32 v73, 0, v73, vcc
	v_cmp_ne_u32_e32 vcc, v74, v65
	v_max3_u32 v66, v66, v72, v73
	s_nop 0
	v_cndmask_b32_e32 v74, 0, v74, vcc
	v_cmp_ne_u32_e32 vcc, v75, v65
	s_nop 1
	v_cndmask_b32_e32 v75, 0, v75, vcc
	v_cmp_ne_u32_e32 vcc, v106, v65
	v_max3_u32 v66, v66, v74, v75
	s_nop 0
	v_cndmask_b32_e32 v106, 0, v106, vcc
	v_cmp_ne_u32_e32 vcc, v108, v65
	s_nop 1
	v_cndmask_b32_e32 v108, 0, v108, vcc
	v_cmp_ne_u32_e32 vcc, v109, v65
	v_max3_u32 v66, v66, v106, v108
	s_nop 0
	v_cndmask_b32_e32 v109, 0, v109, vcc
	v_cmp_ne_u32_e32 vcc, v80, v65
	s_nop 1
	v_cndmask_b32_e32 v80, 0, v80, vcc
	v_cmp_ne_u32_e32 vcc, v81, v65
	v_max3_u32 v66, v66, v109, v80
	s_nop 0
	v_cndmask_b32_e32 v81, 0, v81, vcc
	v_cmp_ne_u32_e32 vcc, v104, v65
	s_nop 1
	v_cndmask_b32_e32 v104, 0, v104, vcc
	v_cmp_ne_u32_e32 vcc, v107, v65
	v_max3_u32 v66, v66, v81, v104
	s_nop 0
	v_cndmask_b32_e32 v107, 0, v107, vcc
	v_cmp_ne_u32_e32 vcc, v105, v65
	s_nop 1
	v_cndmask_b32_e32 v105, 0, v105, vcc
	v_cmp_ne_u32_e32 vcc, v111, v65
	v_max3_u32 v66, v66, v107, v105
	s_nop 0
	v_cndmask_b32_e32 v111, 0, v111, vcc
	v_cmp_ne_u32_e32 vcc, v110, v65
	s_nop 1
	v_cndmask_b32_e32 v110, 0, v110, vcc
	v_max3_u32 v66, v66, v111, v110
	s_nop 1
	v_max_u32_dpp v66, v66, v66 quad_perm:[1,0,3,2] row_mask:0xf bank_mask:0xf
	s_waitcnt lgkmcnt(0)
	s_nop 1
	v_max_u32_dpp v66, v66, v66 quad_perm:[2,3,0,1] row_mask:0xf bank_mask:0xf
	s_waitcnt lgkmcnt(0)
	v_cmp_ne_u32_e64 s[60:61], v112, v66
	v_cmp_ne_u32_e64 s[62:63], v113, v66
	v_cmp_ne_u32_e64 s[64:65], v114, v66
	v_cndmask_b32_e64 v112, 0, v112, s[60:61]
	v_cmp_ne_u32_e64 s[60:61], v67, v66
	v_cndmask_b32_e64 v113, 0, v113, s[62:63]
	v_cndmask_b32_e64 v114, 0, v114, s[64:65]
	v_cndmask_b32_e64 v115, 0, v67, s[60:61]
	v_cmp_ne_u32_e32 vcc, v68, v66
	v_max3_u32 v67, v112, v113, v114
	s_nop 0
	v_cndmask_b32_e32 v68, 0, v68, vcc
	v_cmp_ne_u32_e32 vcc, v69, v66
	v_max3_u32 v67, v67, v115, v68
	s_nop 0
	v_cndmask_b32_e32 v69, 0, v69, vcc
	v_cmp_ne_u32_e32 vcc, v70, v66
	s_nop 1
	v_cndmask_b32_e32 v70, 0, v70, vcc
	v_cmp_ne_u32_e32 vcc, v72, v66
	v_max3_u32 v67, v67, v69, v70
	s_nop 0
	v_cndmask_b32_e32 v72, 0, v72, vcc
	v_cmp_ne_u32_e32 vcc, v73, v66
	s_nop 1
	v_cndmask_b32_e32 v73, 0, v73, vcc
	v_cmp_ne_u32_e32 vcc, v74, v66
	v_max3_u32 v67, v67, v72, v73
	s_nop 0
	v_cndmask_b32_e32 v74, 0, v74, vcc
	v_cmp_ne_u32_e32 vcc, v75, v66
	s_nop 1
	v_cndmask_b32_e32 v75, 0, v75, vcc
	v_cmp_ne_u32_e32 vcc, v106, v66
	v_max3_u32 v67, v67, v74, v75
	s_nop 0
	v_cndmask_b32_e32 v106, 0, v106, vcc
	v_cmp_ne_u32_e32 vcc, v108, v66
	s_nop 1
	v_cndmask_b32_e32 v108, 0, v108, vcc
	v_cmp_ne_u32_e32 vcc, v109, v66
	v_max3_u32 v67, v67, v106, v108
	s_nop 0
	v_cndmask_b32_e32 v109, 0, v109, vcc
	v_cmp_ne_u32_e32 vcc, v80, v66
	s_nop 1
	v_cndmask_b32_e32 v80, 0, v80, vcc
	v_cmp_ne_u32_e32 vcc, v81, v66
	v_max3_u32 v67, v67, v109, v80
	s_nop 0
	v_cndmask_b32_e32 v81, 0, v81, vcc
	v_cmp_ne_u32_e32 vcc, v104, v66
	s_nop 1
	v_cndmask_b32_e32 v104, 0, v104, vcc
	v_cmp_ne_u32_e32 vcc, v107, v66
	v_max3_u32 v67, v67, v81, v104
	s_nop 0
	v_cndmask_b32_e32 v107, 0, v107, vcc
	v_cmp_ne_u32_e32 vcc, v105, v66
	s_nop 1
	v_cndmask_b32_e32 v105, 0, v105, vcc
	v_cmp_ne_u32_e32 vcc, v111, v66
	v_max3_u32 v67, v67, v107, v105
	s_nop 0
	v_cndmask_b32_e32 v111, 0, v111, vcc
	v_cmp_ne_u32_e32 vcc, v110, v66
	s_nop 1
	v_cndmask_b32_e32 v110, 0, v110, vcc
	v_max3_u32 v67, v67, v111, v110
	s_nop 1
	v_max_u32_dpp v67, v67, v67 quad_perm:[1,0,3,2] row_mask:0xf bank_mask:0xf
	s_waitcnt lgkmcnt(0)
	s_nop 1
	v_max_u32_dpp v67, v67, v67 quad_perm:[2,3,0,1] row_mask:0xf bank_mask:0xf
	s_waitcnt lgkmcnt(0)
	v_cmp_ne_u32_e64 s[60:61], v112, v67
	v_cmp_ne_u32_e64 s[62:63], v113, v67
	v_cmp_ne_u32_e64 s[64:65], v114, v67
	v_cndmask_b32_e64 v112, 0, v112, s[60:61]
	v_cmp_ne_u32_e64 s[60:61], v115, v67
	v_cndmask_b32_e64 v113, 0, v113, s[62:63]
	v_cmp_ne_u32_e64 s[62:63], v68, v67
	v_cndmask_b32_e64 v114, 0, v114, s[64:65]
	v_cndmask_b32_e64 v115, 0, v115, s[60:61]
	v_cndmask_b32_e64 v116, 0, v68, s[62:63]
	v_cmp_ne_u32_e32 vcc, v69, v67
	v_max3_u32 v68, v112, v113, v114
	v_max3_u32 v68, v68, v115, v116
	v_cndmask_b32_e32 v69, 0, v69, vcc
	v_cmp_ne_u32_e32 vcc, v70, v67
	s_nop 1
	v_cndmask_b32_e32 v70, 0, v70, vcc
	v_cmp_ne_u32_e32 vcc, v72, v67
	v_max3_u32 v68, v68, v69, v70
	s_nop 0
	v_cndmask_b32_e32 v72, 0, v72, vcc
	v_cmp_ne_u32_e32 vcc, v73, v67
	s_nop 1
	v_cndmask_b32_e32 v73, 0, v73, vcc
	v_cmp_ne_u32_e32 vcc, v74, v67
	v_max3_u32 v68, v68, v72, v73
	s_nop 0
	v_cndmask_b32_e32 v74, 0, v74, vcc
	v_cmp_ne_u32_e32 vcc, v75, v67
	s_nop 1
	v_cndmask_b32_e32 v75, 0, v75, vcc
	v_cmp_ne_u32_e32 vcc, v106, v67
	v_max3_u32 v68, v68, v74, v75
	s_nop 0
	v_cndmask_b32_e32 v106, 0, v106, vcc
	v_cmp_ne_u32_e32 vcc, v108, v67
	s_nop 1
	v_cndmask_b32_e32 v108, 0, v108, vcc
	v_cmp_ne_u32_e32 vcc, v109, v67
	v_max3_u32 v68, v68, v106, v108
	s_nop 0
	v_cndmask_b32_e32 v109, 0, v109, vcc
	v_cmp_ne_u32_e32 vcc, v80, v67
	s_nop 1
	v_cndmask_b32_e32 v80, 0, v80, vcc
	v_cmp_ne_u32_e32 vcc, v81, v67
	v_max3_u32 v68, v68, v109, v80
	s_nop 0
	v_cndmask_b32_e32 v81, 0, v81, vcc
	v_cmp_ne_u32_e32 vcc, v104, v67
	s_nop 1
	v_cndmask_b32_e32 v104, 0, v104, vcc
	v_cmp_ne_u32_e32 vcc, v107, v67
	v_max3_u32 v68, v68, v81, v104
	s_nop 0
	v_cndmask_b32_e32 v107, 0, v107, vcc
	v_cmp_ne_u32_e32 vcc, v105, v67
	s_nop 1
	v_cndmask_b32_e32 v105, 0, v105, vcc
	v_cmp_ne_u32_e32 vcc, v111, v67
	v_max3_u32 v68, v68, v107, v105
	s_nop 0
	v_cndmask_b32_e32 v111, 0, v111, vcc
	v_cmp_ne_u32_e32 vcc, v110, v67
	s_nop 1
	v_cndmask_b32_e32 v110, 0, v110, vcc
	v_max3_u32 v68, v68, v111, v110
	s_nop 1
	v_max_u32_dpp v68, v68, v68 quad_perm:[1,0,3,2] row_mask:0xf bank_mask:0xf
	s_waitcnt lgkmcnt(0)
	s_nop 1
	v_max_u32_dpp v68, v68, v68 quad_perm:[2,3,0,1] row_mask:0xf bank_mask:0xf
	s_waitcnt lgkmcnt(0)
	v_cmp_ne_u32_e32 vcc, v113, v68
	s_nop 1
	v_cndmask_b32_e32 v113, 0, v113, vcc
	v_max_u32_e32 v117, v112, v113
	v_cmp_eq_u32_e32 vcc, v112, v68
	s_nop 1
	v_cndmask_b32_e32 v112, v117, v113, vcc
	v_max_u32_e32 v113, v112, v114
	v_cmp_eq_u32_e32 vcc, v114, v68
	s_nop 1
	v_cndmask_b32_e32 v112, v113, v112, vcc
	v_max_u32_e32 v113, v112, v115
	v_cmp_eq_u32_e32 vcc, v115, v68
	s_nop 1
	v_cndmask_b32_e32 v112, v113, v112, vcc
	v_max_u32_e32 v113, v112, v116
	v_cmp_eq_u32_e32 vcc, v116, v68
	s_nop 1
	v_cndmask_b32_e32 v112, v113, v112, vcc
	v_max_u32_e32 v113, v112, v69
	v_cmp_eq_u32_e32 vcc, v69, v68
	s_nop 1
	v_cndmask_b32_e32 v69, v113, v112, vcc
	v_max_u32_e32 v112, v69, v70
	v_cmp_eq_u32_e32 vcc, v70, v68
	s_nop 1
	v_cndmask_b32_e32 v69, v112, v69, vcc
	v_max_u32_e32 v70, v69, v72
	v_cmp_eq_u32_e32 vcc, v72, v68
	s_nop 1
	v_cndmask_b32_e32 v69, v70, v69, vcc
	v_max_u32_e32 v70, v69, v73
	v_cmp_eq_u32_e32 vcc, v73, v68
	s_nop 1
	v_cndmask_b32_e32 v69, v70, v69, vcc
	v_max_u32_e32 v70, v69, v74
	v_cmp_eq_u32_e32 vcc, v74, v68
	s_nop 1
	v_cndmask_b32_e32 v69, v70, v69, vcc
	v_max_u32_e32 v70, v69, v75
	v_cmp_eq_u32_e32 vcc, v75, v68
	s_nop 1
	v_cndmask_b32_e32 v69, v70, v69, vcc
	v_max_u32_e32 v70, v69, v106
	v_cmp_eq_u32_e32 vcc, v106, v68
	s_nop 1
	v_cndmask_b32_e32 v69, v70, v69, vcc
	v_max_u32_e32 v70, v69, v108
	v_cmp_eq_u32_e32 vcc, v108, v68
	s_nop 1
	v_cndmask_b32_e32 v69, v70, v69, vcc
	v_max_u32_e32 v70, v69, v109
	v_cmp_eq_u32_e32 vcc, v109, v68
	s_nop 1
	v_cndmask_b32_e32 v69, v70, v69, vcc
	v_max_u32_e32 v70, v69, v80
	v_cmp_eq_u32_e32 vcc, v80, v68
	s_nop 1
	v_cndmask_b32_e32 v69, v70, v69, vcc
	v_max_u32_e32 v70, v69, v81
	v_cmp_eq_u32_e32 vcc, v81, v68
	s_nop 1
	v_cndmask_b32_e32 v69, v70, v69, vcc
	v_max_u32_e32 v70, v69, v104
	v_cmp_eq_u32_e32 vcc, v104, v68
	s_nop 1
	v_cndmask_b32_e32 v69, v70, v69, vcc
	v_max_u32_e32 v70, v69, v107
	v_cmp_eq_u32_e32 vcc, v107, v68
	v_bitop3_b32 v107, v63, 15, v63 bitop3:0xc
	v_add_u32_e32 v107, v86, v107
	v_cndmask_b32_e32 v69, v70, v69, vcc
	v_max_u32_e32 v70, v69, v105
	v_cmp_eq_u32_e32 vcc, v105, v68
	v_bitop3_b32 v105, v62, 15, v62 bitop3:0xc
	v_add_u32_e32 v105, v86, v105
	v_cndmask_b32_e32 v69, v70, v69, vcc
	v_max_u32_e32 v70, v69, v111
	v_cmp_eq_u32_e32 vcc, v111, v68
	s_nop 1
	v_cndmask_b32_e32 v69, v70, v69, vcc
	v_max_u32_e32 v70, v69, v110
	v_cmp_eq_u32_e32 vcc, v110, v68
	s_nop 1
	v_cndmask_b32_e32 v69, v70, v69, vcc
	v_cmp_lt_i32_e32 vcc, -1, v59
	s_nop 1
	v_max_u32_dpp v69, v69, v69 quad_perm:[1,0,3,2] row_mask:0xf bank_mask:0xf
	s_waitcnt lgkmcnt(0)
	v_cndmask_b32_e64 v72, v101, -1, vcc
	v_cmp_lt_i32_e32 vcc, -1, v61
	s_nop 1
	v_mov_b32_dpp v70, v69 quad_perm:[2,3,0,1] row_mask:0xf bank_mask:0xf
	v_bitop3_b32 v72, v72, v59, s58 bitop3:0x78
	v_cndmask_b32_e64 v73, v101, -1, vcc
	v_cmp_lt_i32_e32 vcc, -1, v102
	v_bitop3_b32 v73, v73, v61, s58 bitop3:0x78
	s_nop 0
	v_cndmask_b32_e64 v74, v101, -1, vcc
	v_cmp_lt_i32_e32 vcc, -1, v103
	v_bitop3_b32 v74, v74, v102, s58 bitop3:0x78
	s_nop 0
	v_cndmask_b32_e64 v75, v101, -1, vcc
	v_cmp_lt_i32_e32 vcc, -1, v76
	v_bitop3_b32 v75, v75, v103, s58 bitop3:0x78
	s_nop 0
	v_cndmask_b32_e64 v80, v101, -1, vcc
	v_cmp_lt_i32_e32 vcc, -1, v77
	v_bitop3_b32 v80, v80, v76, s58 bitop3:0x78
	s_nop 0
	v_cndmask_b32_e64 v81, v101, -1, vcc
	v_cmp_lt_i32_e32 vcc, -1, v78
	v_bitop3_b32 v81, v81, v77, s58 bitop3:0x78
	s_nop 0
	v_cndmask_b32_e64 v104, v101, -1, vcc
	v_cmp_lt_i32_e32 vcc, -1, v79
	v_bitop3_b32 v112, v104, v78, s58 bitop3:0x78
	s_nop 0
	v_cndmask_b32_e64 v104, v101, -1, vcc
	v_cmp_lt_i32_e32 vcc, -1, v62
	v_bitop3_b32 v113, v104, v79, s58 bitop3:0x78
	v_not_b32_e32 v104, v62
	v_cndmask_b32_e64 v106, v101, -1, vcc
	v_cmp_lt_i32_e32 vcc, -1, v63
	v_bitop3_b32 v62, v106, v62, s58 bitop3:0x78
	v_not_b32_e32 v106, v63
	v_cndmask_b32_e64 v108, v101, -1, vcc
	v_bitop3_b32 v63, v108, v63, s58 bitop3:0x78
	v_not_b32_e32 v108, v64
	v_bfe_u32 v108, v108, 4, 4
	v_add_u32_e32 v114, v86, v108
	v_bitop3_b32 v108, v64, 15, v64 bitop3:0xc
	v_cmp_lt_i32_e32 vcc, -1, v64
	v_add_u32_e32 v115, v86, v108
	v_bfe_u32 v104, v104, 4, 4
	v_cndmask_b32_e64 v108, v101, -1, vcc
	v_bitop3_b32 v64, v108, v64, s58 bitop3:0x78
	v_not_b32_e32 v108, v65
	v_bfe_u32 v106, v106, 4, 4
	v_bfe_u32 v108, v108, 4, 4
	v_add_u32_e32 v104, v86, v104
	v_add_u32_e32 v106, v86, v106
	v_add_u32_e32 v116, v86, v108
	v_bitop3_b32 v108, v65, 15, v65 bitop3:0xc
	v_cmp_lt_i32_e32 vcc, -1, v65
	v_add_u32_e32 v117, v86, v108
	ds_read_u8 v110, v104
	ds_read_u8 v111, v105 offset:16
	ds_read_u8 v108, v106
	ds_read_u8 v109, v107 offset:16
	ds_read_u8 v106, v114
	ds_read_u8 v107, v115 offset:16
	ds_read_u8 v104, v116
	ds_read_u8 v105, v117 offset:16
	v_cndmask_b32_e64 v114, v101, -1, vcc
	v_cmp_lt_i32_e32 vcc, -1, v66
	v_bitop3_b32 v65, v114, v65, s58 bitop3:0x78
	v_not_b32_e32 v114, v66
	v_cndmask_b32_e64 v116, v101, -1, vcc
	v_bitop3_b32 v115, v66, 15, v66 bitop3:0xc
	v_bitop3_b32 v116, v116, v66, s58 bitop3:0x78
	v_not_b32_e32 v66, v67
	v_bfe_u32 v66, v66, 4, 4
	v_add_u32_e32 v117, v86, v66
	v_bitop3_b32 v66, v67, 15, v67 bitop3:0xc
	v_cmp_lt_i32_e32 vcc, -1, v67
	v_add_u32_e32 v127, v86, v66
	v_sub_f32_e32 v62, v62, v72
	v_cndmask_b32_e64 v66, v101, -1, vcc
	v_bitop3_b32 v118, v66, v67, s58 bitop3:0x78
	v_not_b32_e32 v66, v68
	v_bfe_u32 v66, v66, 4, 4
	v_add_u32_e32 v128, v86, v66
	v_bitop3_b32 v66, v68, 15, v68 bitop3:0xc
	v_cmp_lt_i32_e32 vcc, -1, v68
	v_add_u32_e32 v129, v86, v66
	v_mul_f32_e32 v62, 0x3fb8aa3b, v62
	v_cndmask_b32_e64 v66, v101, -1, vcc
	v_bitop3_b32 v119, v66, v68, s58 bitop3:0x78
	s_waitcnt lgkmcnt(8)
	v_max_u32_e32 v66, v69, v70
	v_not_b32_e32 v67, v66
	v_bfe_u32 v67, v67, 4, 4
	v_add_u32_e32 v70, v86, v67
	v_bitop3_b32 v67, v66, 15, v66 bitop3:0xc
	v_cmp_lt_i32_e32 vcc, -1, v66
	v_add_u32_e32 v130, v86, v67
	v_bfe_u32 v114, v114, 4, 4
	v_cndmask_b32_e64 v67, v101, -1, vcc
	v_bitop3_b32 v131, v67, v66, s58 bitop3:0x78
	v_sub_f32_e32 v66, v72, v72
	v_mul_f32_e32 v66, 0x3fb8aa3b, v66
	v_exp_f32_e32 v124, v66
	v_sub_f32_e32 v66, v73, v72
	v_mul_f32_e32 v66, 0x3fb8aa3b, v66
	v_exp_f32_e32 v123, v66
	v_sub_f32_e32 v66, v74, v72
	v_sub_f32_e32 v67, v80, v72
	v_mul_f32_e32 v66, 0x3fb8aa3b, v66
	v_mul_f32_e32 v67, 0x3fb8aa3b, v67
	v_exp_f32_e32 v125, v66
	v_sub_f32_e32 v66, v75, v72
	v_exp_f32_e32 v80, v67
	v_sub_f32_e32 v67, v81, v72
	v_mul_f32_e32 v66, 0x3fb8aa3b, v66
	v_mul_f32_e32 v67, 0x3fb8aa3b, v67
	v_exp_f32_e32 v126, v66
	v_exp_f32_e32 v120, v67
	v_sub_f32_e32 v67, v112, v72
	v_add_f32_e32 v66, 0, v124
	v_mul_f32_e32 v67, 0x3fb8aa3b, v67
	v_add_f32_e32 v66, v66, v123
	v_exp_f32_e32 v121, v67
	v_sub_f32_e32 v67, v113, v72
	v_add_f32_e32 v66, v66, v125
	v_mul_f32_e32 v67, 0x3fb8aa3b, v67
	v_add_f32_e32 v66, v66, v126
	v_exp_f32_e32 v122, v67
	v_add_f32_e32 v66, v66, v80
	v_add_f32_e32 v66, v66, v120
	v_add_f32_e32 v66, v66, v121
	v_add_f32_e32 v73, v66, v122
	v_exp_f32_e32 v66, v62
	v_sub_f32_e32 v62, v63, v72
	v_mul_f32_e32 v62, 0x3fb8aa3b, v62
	v_exp_f32_e32 v67, v62
	v_sub_f32_e32 v62, v64, v72
	v_mul_f32_e32 v62, 0x3fb8aa3b, v62
	v_exp_f32_e32 v68, v62
	v_sub_f32_e32 v62, v65, v72
	v_mul_f32_e32 v62, 0x3fb8aa3b, v62
	v_exp_f32_e32 v69, v62
	v_add_f32_e32 v62, v73, v66
	v_add_f32_e32 v62, v62, v67
	v_add_f32_e32 v62, v62, v68
	v_add_f32_e32 v73, v62, v69
	v_sub_f32_e32 v62, v116, v72
	v_mul_f32_e32 v62, 0x3fb8aa3b, v62
	v_sub_f32_e32 v63, v118, v72
	v_exp_f32_e32 v62, v62
	v_mul_f32_e32 v63, 0x3fb8aa3b, v63
	v_sub_f32_e32 v64, v119, v72
	v_exp_f32_e32 v63, v63
	v_mul_f32_e32 v64, 0x3fb8aa3b, v64
	v_sub_f32_e32 v65, v131, v72
	v_exp_f32_e32 v64, v64
	v_mul_f32_e32 v65, 0x3fb8aa3b, v65
	v_exp_f32_e32 v65, v65
	v_add_f32_e32 v72, v73, v62
	v_add_f32_e32 v72, v72, v63
	v_add_f32_e32 v72, v72, v64
	v_add_f32_e32 v73, v72, v65
	v_div_scale_f32 v74, s[28:29], v73, v73, 1.0
	v_rcp_f32_e32 v75, v74
	v_add_u32_e32 v114, v86, v114
	v_add_u32_e32 v115, v86, v115
	ds_read_u8 v118, v114
	ds_read_u8 v119, v115 offset:16
	ds_read_u8 v116, v117
	ds_read_u8 v117, v127 offset:16
	ds_read_u8 v114, v128
	ds_read_u8 v115, v129 offset:16
	ds_read_u8 v112, v70
	ds_read_u8 v113, v130 offset:16
	v_fma_f32 v70, -v74, v75, 1.0
	v_fmac_f32_e32 v75, v70, v75
	v_div_scale_f32 v70, vcc, 1.0, v73, 1.0
	v_mul_f32_e32 v81, v70, v75
	v_fma_f32 v127, -v74, v81, v70
	v_fmac_f32_e32 v81, v127, v75
	v_fma_f32 v70, -v74, v81, v70
	v_add_u32_e32 v72, s34, v82
	v_div_fmas_f32 v70, v70, v75, v81
	v_div_fixup_f32 v70, v70, v73, 1.0
	v_ashrrev_i32_e32 v73, 31, v72
	v_lshlrev_b64 v[72:73], 9, v[72:73]
	v_lshl_add_u64 v[74:75], s[20:21], 0, v[72:73]
	v_lshl_add_u64 v[72:73], s[22:23], 0, v[72:73]
	v_lshl_add_u64 v[74:75], v[74:75], 0, s[24:25]
	v_lshl_add_u64 v[72:73], v[72:73], 0, s[24:25]
	v_cmp_lt_i32_e32 vcc, 0, v83
	s_mov_b64 s[28:29], 0
	s_and_saveexec_b64 s[30:31], vcc
	s_xor_b64 s[30:31], exec, s[30:31]
	s_cbranch_execz .LBB0_847
	v_cmp_eq_u32_e32 vcc, 1, v83
	s_and_saveexec_b64 s[34:35], vcc
	s_cbranch_execz .LBB0_846
	v_not_b32_e32 v59, v79
	v_not_b32_e32 v81, v77
	v_not_b32_e32 v102, v76
	v_bfe_u32 v59, v59, 4, 4
	v_bitop3_b32 v61, v79, 15, v79 bitop3:0xc
	v_not_b32_e32 v79, v78
	v_bitop3_b32 v78, v78, 15, v78 bitop3:0xc
	v_bfe_u32 v81, v81, 4, 4
	v_bitop3_b32 v77, v77, 15, v77 bitop3:0xc
	v_bfe_u32 v102, v102, 4, 4
	v_bitop3_b32 v76, v76, 15, v76 bitop3:0xc
	v_add_u32_e32 v59, v86, v59
	v_add_u32_e32 v61, v86, v61
	v_bfe_u32 v79, v79, 4, 4
	v_add_u32_e32 v78, v86, v78
	v_add_u32_e32 v81, v86, v81
	v_add_u32_e32 v77, v86, v77
	v_add_u32_e32 v102, v86, v102
	v_add_u32_e32 v76, v86, v76
	v_add_u32_e32 v79, v86, v79
	ds_read_u8 v59, v59
	ds_read_u8 v61, v61 offset:16
	ds_read_u8 v103, v79
	ds_read_u8 v78, v78 offset:16
	ds_read_u8 v81, v81
	ds_read_u8 v77, v77 offset:16
	ds_read_u8 v102, v102
	ds_read_u8 v76, v76 offset:16
	s_waitcnt lgkmcnt(6)
	v_lshl_add_u32 v79, v59, 7, v61
	s_waitcnt lgkmcnt(4)
	v_lshl_add_u32 v78, v103, 7, v78
	s_waitcnt lgkmcnt(2)
	v_lshl_add_u32 v77, v81, 7, v77
	v_mul_f32_e32 v59, v80, v70
	s_waitcnt lgkmcnt(0)
	v_lshl_add_u32 v76, v102, 7, v76
	s_mov_b64 s[28:29], exec
	global_store_dwordx4 v[74:75], v[76:79], off offset:16
	global_store_dword v[72:73], v59, off offset:16
